# attention loops: row-sum chains start from the first pair (no +0 adds), self-max canonicalisation after the lane swap dropped
# baseline (speedup 1.0000x reference)
; #define MFMA32(a, b, c) __builtin_amdgcn_mfma_f32_32x32x16_bf16((a), (b), (c), 0, 0, 0)
; DI int crow(int reg, int h) { return (reg & 3) + 8 * (reg >> 2) + 4 * h; }
; template <int MODE>
; DI void attn_mfma(const Params& p, int l, int b, int hd, int qb, unsigned char* smem) {
;     ...
; #pragma unroll
;     for (int ks = 0; ks < KS; ++ks) {
;       const int kk = mp * 2 + ks;
;       const int key0 = r, key1 = 32 + r;
;       const int o0 = key0 * 128 + (((2 * kk + h2) ^ ((key0 >> 1) & 7)) << 4), o1 = key1 * 128 + (((2 * kk + h2) ^ ((key1 >> 1) & 7)) << 4);
;       SA0 = MFMA32(*(const bf16x8*)(sK + o0), qf[ks], SA0);
;       SA1 = MFMA32(*(const bf16x8*)(sK + o1), qf[ks], SA1);
;       SB0 = MFMA32(*(const bf16x8*)(sK + 16896 + o0), qf[ks], SB0);
;       SB1 = MFMA32(*(const bf16x8*)(sK + 16896 + o1), qf[ks], SB1);
;     }
; #pragma unroll
;     for (int hf = 0; hf < 2; ++hf) {
;     const unsigned char* sVc = sV + hf * 16896;
;     const int tbcur = tile_base(j + hf);
;     f32x16 S[2];
;     S[0] = hf == 0 ? SA0 : SB0;
;     S[1] = hf == 0 ? SA1 : SB1;
;     if (MODE == 1 && j + hf >= 4) {
;       const int iq = tq - NCTX;
;       const int jb = tbcur - NCTX;
; #pragma unroll
;       for (int mt = 0; mt < 2; ++mt)
; #pragma unroll
;         for (int i = 0; i < 16; ++i) {
;           const int dd = iq - (jb + mt * 32 + crow(i, h2));
;           if (dd > 128 || dd < -128) S[mt][i] = -1e30f;
;         }
;     }
;     float mx = -1e30f;
; #pragma unroll
;     for (int mt = 0; mt < 2; ++mt)
; #pragma unroll
;       for (int i = 0; i < 16; ++i) mx = fmaxf(mx, S[mt][i]);
;     mx = fmaxf(mx, __shfl_xor(mx, 32));
;     const float zmx = mx * cexp;
;     if (__any(zmx > mrun + 8.f)) {
;       const float mnew = fmaxf(mrun, zmx);
;       const float alpha = __builtin_amdgcn_exp2f(mrun - mnew);
;       mrun = mnew;
;       lsum *= alpha;
;       const f32x2 al2 = {alpha, alpha};
; #pragma unroll
;       for (int vt = 0; vt < 2; ++vt)
; #pragma unroll
;         for (int i = 0; i < 8; ++i) {
;           f32x2 o = {O[vt][2 * i], O[vt][2 * i + 1]};
;           o = o * al2;
;           O[vt][2 * i] = o.x; O[vt][2 * i + 1] = o.y;
;         }
;     }
.LBB0_582:
	s_mov_b32 s5, 0xf149f2ca
	s_mov_b32 s8, 0x3e8293ee
	s_waitcnt lgkmcnt(6)
	v_mfma_f32_32x32x16_bf16 v[80:95], v[204:207], v[96:99], 0
	v_mfma_f32_32x32x16_bf16 v[80:95], v[208:211], v[100:103], v[80:95]
	s_waitcnt lgkmcnt(4)
	v_mfma_f32_32x32x16_bf16 v[64:79], v[212:215], v[96:99], 0
	v_mfma_f32_32x32x16_bf16 v[64:79], v[216:219], v[100:103], v[64:79]
	s_waitcnt lgkmcnt(0)
	v_mfma_f32_32x32x16_bf16 v[48:63], v[220:223], v[96:99], 0
	ds_read2_b64 v[204:207], v236 offset1:2
	ds_read2_b64 v[208:211], v237 offset0:32 offset1:34
	ds_read2_b64 v[212:215], v236 offset0:4 offset1:6
	ds_read2_b64 v[216:219], v237 offset0:36 offset1:38
	v_mfma_f32_32x32x16_bf16 v[48:63], v[224:227], v[100:103], v[48:63]
	s_nop 1
	v_max3_f32 v146, v80, s5, v81
	v_max3_f32 v146, v146, v82, v83
	v_max3_f32 v146, v146, v84, v85
	v_max3_f32 v146, v146, v86, v87
	v_max3_f32 v146, v146, v88, v89
	v_max3_f32 v146, v146, v90, v91
	v_max3_f32 v146, v146, v92, v93
	v_max3_f32 v146, v146, v94, v95
	v_mfma_f32_32x32x16_bf16 v[32:47], v[228:231], v[96:99], 0
	v_max3_f32 v146, v146, v64, v65
	v_max3_f32 v146, v146, v66, v67
	v_max3_f32 v146, v146, v68, v69
	v_max3_f32 v146, v146, v70, v71
	v_mfma_f32_32x32x16_bf16 v[32:47], v[232:235], v[100:103], v[32:47]
	v_max3_f32 v146, v146, v72, v73
	v_max3_f32 v146, v146, v74, v75
	v_max3_f32 v146, v146, v76, v77
	v_max3_f32 v146, v146, v78, v79
	v_mov_b32_e32 v147, v146
	s_nop 1
	v_permlane32_swap_b32_e32 v147, v146
	ds_read2_b64 v[220:223], v236 offset0:8 offset1:10
	ds_read2_b64 v[224:227], v237 offset0:40 offset1:42
	ds_read2_b64 v[228:231], v236 offset0:12 offset1:14
	ds_read2_b64 v[232:235], v237 offset0:44 offset1:46
	s_waitcnt lgkmcnt(4)
	v_max_f32_e32 v146, v146, v147
	v_mul_f32_e32 v147, 0x3e8293ee, v146
	v_add_f32_e32 v146, 0x41000000, v140
	v_cmp_gt_f32_e32 vcc, v147, v146
	s_cbranch_vccz .Laa_nra
	v_max_f32_e32 v146, v147, v147
	v_max_f32_e32 v147, v140, v140
	v_max_f32_e32 v147, v147, v146
	v_sub_f32_e32 v140, v140, v147
	v_exp_f32_e32 v140, v140
	v_add_f32_e32 v146, 0x41000000, v147
	v_pk_mul_f32 v[18:19], v[18:19], v[140:141] op_sel_hi:[1,0]
	v_pk_mul_f32 v[20:21], v[20:21], v[140:141] op_sel_hi:[1,0]
	v_pk_mul_f32 v[22:23], v[22:23], v[140:141] op_sel_hi:[1,0]
	v_pk_mul_f32 v[24:25], v[24:25], v[140:141] op_sel_hi:[1,0]
	v_pk_mul_f32 v[26:27], v[26:27], v[140:141] op_sel_hi:[1,0]
	v_pk_mul_f32 v[28:29], v[28:29], v[140:141] op_sel_hi:[1,0]
	v_pk_mul_f32 v[16:17], v[16:17], v[140:141] op_sel_hi:[1,0]
	v_pk_mul_f32 v[30:31], v[30:31], v[140:141] op_sel_hi:[1,0]
	v_pk_mul_f32 v[0:1], v[0:1], v[140:141] op_sel_hi:[1,0]
	v_pk_mul_f32 v[2:3], v[2:3], v[140:141] op_sel_hi:[1,0]
	v_pk_mul_f32 v[4:5], v[4:5], v[140:141] op_sel_hi:[1,0]
	v_pk_mul_f32 v[6:7], v[6:7], v[140:141] op_sel_hi:[1,0]
	v_pk_mul_f32 v[8:9], v[8:9], v[140:141] op_sel_hi:[1,0]
	v_pk_mul_f32 v[10:11], v[10:11], v[140:141] op_sel_hi:[1,0]
	v_pk_mul_f32 v[12:13], v[12:13], v[140:141] op_sel_hi:[1,0]
	v_pk_mul_f32 v[14:15], v[14:15], v[140:141] op_sel_hi:[1,0]
	v_mul_f32_e32 v200, v200, v140
	v_mov_b32_e32 v140, v147
; DI unsigned pk2(float a, float b) { hwf32x2 f = {a, b}; hwbf16x2 r = __builtin_convertvector(f, hwbf16x2); return __builtin_bit_cast(unsigned, r); }
; #define MFMA32(a, b, c) __builtin_amdgcn_mfma_f32_32x32x16_bf16((a), (b), (c), 0, 0, 0)
; template <int MODE>
; DI void attn_mfma(const Params& p, int l, int b, int hd, int qb, unsigned char* smem) {
;     ...
;     float mx = -1e30f;
; #pragma unroll
;     for (int mt = 0; mt < 2; ++mt)
; #pragma unroll
;       for (int i = 0; i < 16; ++i) mx = fmaxf(mx, S[mt][i]);
;     mx = fmaxf(mx, __shfl_xor(mx, 32));
;     const float zmx = mx * cexp;
;     if (__any(zmx > mrun + 8.f)) {
;       const float mnew = fmaxf(mrun, zmx);
;       const float alpha = __builtin_amdgcn_exp2f(mrun - mnew);
;       mrun = mnew;
;       lsum *= alpha;
;       const f32x2 al2 = {alpha, alpha};
; #pragma unroll
;       for (int vt = 0; vt < 2; ++vt)
; #pragma unroll
;         for (int i = 0; i < 8; ++i) {
;           f32x2 o = {O[vt][2 * i], O[vt][2 * i + 1]};
;           o = o * al2;
;           O[vt][2 * i] = o.x; O[vt][2 * i + 1] = o.y;
;         }
;     }
;     const f32x2 c2 = {cexp, cexp}, m2 = {mrun, mrun};
;     f32x2 ps2 = {0.f, 0.f};
;     unsigned pk[2][8];
; #pragma unroll
;     for (int mt = 0; mt < 2; ++mt)
; #pragma unroll
;       for (int i = 0; i < 8; ++i) {
;         f32x2 z = {S[mt][2 * i], S[mt][2 * i + 1]};
;         z = z * c2 - m2;
;         f32x2 pv = {__builtin_amdgcn_exp2f(z.x), __builtin_amdgcn_exp2f(z.y)};
;         ps2 = ps2 + pv;
;         pk[mt][i] = pk2(pv.x, pv.y);
;       }
;     lsum += ps2.x + ps2.y;
; #pragma unroll
;     for (int mt = 0; mt < 2; ++mt)
; #pragma unroll
;       for (int s = 0; s < 2; ++s) {
;         const uint4 pu = make_uint4(pk[mt][4 * s], pk[mt][4 * s + 1], pk[mt][4 * s + 2], pk[mt][4 * s + 3]);
;         const bf16x8 pf = __builtin_bit_cast(bf16x8, pu);
; #pragma unroll
;         for (int vt = 0; vt < 2; ++vt) {
;           const unsigned char* bp = sVc + (vt * 32 + r) * 136 + (mt * 32 + 16 * s + 4 * h2) * 2;
;           const uint2 lo = *(const uint2*)(bp);
;           const uint2 hi = *(const uint2*)(bp + 16);
;           const uint4 u = make_uint4(lo.x, lo.y, hi.x, hi.y);
;           O[vt] = MFMA32(__builtin_bit_cast(bf16x8, u), pf, O[vt]);
;         }
;       }
.Laa_nra:
	v_fma_f32 v80, v80, s8, -v140
	v_fma_f32 v81, v81, s8, -v140
	v_fma_f32 v82, v82, s8, -v140
	v_fma_f32 v83, v83, s8, -v140
	v_fma_f32 v84, v84, s8, -v140
	v_fma_f32 v85, v85, s8, -v140
	v_fma_f32 v86, v86, s8, -v140
	v_fma_f32 v87, v87, s8, -v140
	v_exp_f32_e32 v80, v80
	v_exp_f32_e32 v81, v81
	v_exp_f32_e32 v82, v82
	v_exp_f32_e32 v83, v83
	v_exp_f32_e32 v84, v84
	v_exp_f32_e32 v85, v85
	v_exp_f32_e32 v86, v86
	v_exp_f32_e32 v87, v87
	v_add_f32_e32 v148, v82, v80
	v_add_f32_e32 v149, v83, v81
	v_add_f32_e32 v148, v84, v148
	v_add_f32_e32 v149, v85, v149
	v_add_f32_e32 v148, v86, v148
	v_add_f32_e32 v149, v87, v149
	v_cvt_pk_bf16_f32 v80, v80, v81
	v_cvt_pk_bf16_f32 v81, v82, v83
	v_cvt_pk_bf16_f32 v82, v84, v85
	v_cvt_pk_bf16_f32 v83, v86, v87
	v_fma_f32 v88, v88, s8, -v140
	v_fma_f32 v89, v89, s8, -v140
	v_fma_f32 v90, v90, s8, -v140
	v_mfma_f32_32x32x16_bf16 v[16:31], v[204:207], v[80:83], v[16:31]
	v_fma_f32 v91, v91, s8, -v140
	v_fma_f32 v92, v92, s8, -v140
	v_fma_f32 v93, v93, s8, -v140
	v_fma_f32 v94, v94, s8, -v140
	v_fma_f32 v95, v95, s8, -v140
	v_exp_f32_e32 v88, v88
	v_exp_f32_e32 v89, v89
	v_exp_f32_e32 v90, v90
	v_exp_f32_e32 v91, v91
	v_exp_f32_e32 v92, v92
	v_exp_f32_e32 v93, v93
	v_exp_f32_e32 v94, v94
	v_mfma_f32_32x32x16_bf16 v[0:15], v[208:211], v[80:83], v[0:15]
	v_exp_f32_e32 v95, v95
	v_add_f32_e32 v148, v88, v148
	v_add_f32_e32 v149, v89, v149
	v_add_f32_e32 v148, v90, v148
	v_add_f32_e32 v149, v91, v149
	v_add_f32_e32 v148, v92, v148
	v_add_f32_e32 v149, v93, v149
	v_add_f32_e32 v148, v94, v148
	v_add_f32_e32 v149, v95, v149
	v_cvt_pk_bf16_f32 v88, v88, v89
	v_cvt_pk_bf16_f32 v89, v90, v91
	v_cvt_pk_bf16_f32 v90, v92, v93
	v_cvt_pk_bf16_f32 v91, v94, v95
	v_fma_f32 v64, v64, s8, -v140
	v_fma_f32 v65, v65, s8, -v140
	v_fma_f32 v66, v66, s8, -v140
	v_mfma_f32_32x32x16_bf16 v[16:31], v[212:215], v[88:91], v[16:31]
	v_fma_f32 v67, v67, s8, -v140
	v_fma_f32 v68, v68, s8, -v140
	v_fma_f32 v69, v69, s8, -v140
	v_fma_f32 v70, v70, s8, -v140
	v_fma_f32 v71, v71, s8, -v140
	v_exp_f32_e32 v64, v64
	v_exp_f32_e32 v65, v65
	v_exp_f32_e32 v66, v66
	v_exp_f32_e32 v67, v67
	v_exp_f32_e32 v68, v68
	v_exp_f32_e32 v69, v69
	v_exp_f32_e32 v70, v70
	v_mfma_f32_32x32x16_bf16 v[0:15], v[216:219], v[88:91], v[0:15]
	v_exp_f32_e32 v71, v71
	v_add_f32_e32 v148, v64, v148
	v_add_f32_e32 v149, v65, v149
	v_add_f32_e32 v148, v66, v148
	v_add_f32_e32 v149, v67, v149
	v_add_f32_e32 v148, v68, v148
	v_add_f32_e32 v149, v69, v149
	v_add_f32_e32 v148, v70, v148
	v_add_f32_e32 v149, v71, v149
	v_cvt_pk_bf16_f32 v84, v64, v65
	v_cvt_pk_bf16_f32 v85, v66, v67
	v_cvt_pk_bf16_f32 v86, v68, v69
	v_cvt_pk_bf16_f32 v87, v70, v71
	v_fma_f32 v72, v72, s8, -v140
	v_fma_f32 v73, v73, s8, -v140
	v_fma_f32 v74, v74, s8, -v140
	s_waitcnt lgkmcnt(0)
	v_mfma_f32_32x32x16_bf16 v[16:31], v[220:223], v[84:87], v[16:31]
	v_fma_f32 v75, v75, s8, -v140
	v_fma_f32 v76, v76, s8, -v140
	v_fma_f32 v77, v77, s8, -v140
	v_fma_f32 v78, v78, s8, -v140
	v_fma_f32 v79, v79, s8, -v140
	v_exp_f32_e32 v72, v72
	v_exp_f32_e32 v73, v73
	v_exp_f32_e32 v74, v74
	v_exp_f32_e32 v75, v75
	v_exp_f32_e32 v76, v76
	v_exp_f32_e32 v77, v77
	v_exp_f32_e32 v78, v78
	v_mfma_f32_32x32x16_bf16 v[0:15], v[224:227], v[84:87], v[0:15]
	v_exp_f32_e32 v79, v79
	v_add_f32_e32 v148, v72, v148
	v_add_f32_e32 v149, v73, v149
	v_add_f32_e32 v148, v74, v148
	v_add_f32_e32 v149, v75, v149
	v_add_f32_e32 v148, v76, v148
	v_add_f32_e32 v149, v77, v149
	v_add_f32_e32 v148, v78, v148
	v_add_f32_e32 v149, v79, v149
	v_cvt_pk_bf16_f32 v64, v72, v73
	v_cvt_pk_bf16_f32 v65, v74, v75
	v_cvt_pk_bf16_f32 v66, v76, v77
	v_cvt_pk_bf16_f32 v67, v78, v79
	v_add_f32_e32 v151, v148, v149
	v_add_f32_e32 v152, v200, v151
	v_mfma_f32_32x32x16_bf16 v[16:31], v[228:231], v[64:67], v[16:31]
	v_max3_f32 v150, v48, s5, v49
	v_max3_f32 v150, v150, v50, v51
	v_max3_f32 v150, v150, v52, v53
	v_max3_f32 v150, v150, v54, v55
	v_max3_f32 v150, v150, v56, v57
	v_max3_f32 v150, v150, v58, v59
	v_max3_f32 v150, v150, v60, v61
	v_max3_f32 v150, v150, v62, v63
	v_mfma_f32_32x32x16_bf16 v[0:15], v[232:235], v[64:67], v[0:15]
	v_max3_f32 v150, v150, v32, v33
	v_max3_f32 v150, v150, v34, v35
	v_max3_f32 v150, v150, v36, v37
	v_max3_f32 v150, v150, v38, v39
	v_max3_f32 v150, v150, v40, v41
	v_max3_f32 v150, v150, v42, v43
	v_max3_f32 v150, v150, v44, v45
	v_max3_f32 v150, v150, v46, v47
	v_mov_b32_e32 v151, v150
	s_nop 1
	v_permlane32_swap_b32_e32 v151, v150
	ds_read2_b64 v[204:207], v238 offset0:64 offset1:66
	ds_read2_b64 v[208:211], v239 offset0:96 offset1:98
	ds_read2_b64 v[212:215], v238 offset0:68 offset1:70
	ds_read2_b64 v[216:219], v239 offset0:100 offset1:102
	ds_read2_b64 v[220:223], v238 offset0:72 offset1:74
	ds_read2_b64 v[224:227], v239 offset0:104 offset1:106
	ds_read2_b64 v[228:231], v238 offset0:76 offset1:78
	ds_read2_b64 v[232:235], v239 offset0:108 offset1:110
	s_waitcnt lgkmcnt(8)
	v_max_f32_e32 v150, v150, v151
	v_mul_f32_e32 v150, 0x3e8293ee, v150
	v_cmp_gt_f32_e32 vcc, v150, v146
	s_cbranch_vccz .Laa_nrb
	v_max_f32_e32 v150, v150, v150
	v_max_f32_e32 v151, v140, v140
	v_max_f32_e32 v150, v151, v150
	v_sub_f32_e32 v151, v140, v150
	v_exp_f32_e32 v154, v151
	v_mov_b32_e32 v140, v150
	v_pk_mul_f32 v[16:17], v[16:17], v[154:155] op_sel_hi:[1,0]
	v_pk_mul_f32 v[18:19], v[18:19], v[154:155] op_sel_hi:[1,0]
	v_pk_mul_f32 v[20:21], v[20:21], v[154:155] op_sel_hi:[1,0]
	v_pk_mul_f32 v[22:23], v[22:23], v[154:155] op_sel_hi:[1,0]
	v_pk_mul_f32 v[24:25], v[24:25], v[154:155] op_sel_hi:[1,0]
	v_pk_mul_f32 v[26:27], v[26:27], v[154:155] op_sel_hi:[1,0]
	v_pk_mul_f32 v[28:29], v[28:29], v[154:155] op_sel_hi:[1,0]
	v_pk_mul_f32 v[30:31], v[30:31], v[154:155] op_sel_hi:[1,0]
	v_pk_mul_f32 v[0:1], v[0:1], v[154:155] op_sel_hi:[1,0]
	v_pk_mul_f32 v[2:3], v[2:3], v[154:155] op_sel_hi:[1,0]
	v_pk_mul_f32 v[4:5], v[4:5], v[154:155] op_sel_hi:[1,0]
	v_pk_mul_f32 v[6:7], v[6:7], v[154:155] op_sel_hi:[1,0]
	v_pk_mul_f32 v[8:9], v[8:9], v[154:155] op_sel_hi:[1,0]
	v_pk_mul_f32 v[10:11], v[10:11], v[154:155] op_sel_hi:[1,0]
	v_pk_mul_f32 v[12:13], v[12:13], v[154:155] op_sel_hi:[1,0]
	v_pk_mul_f32 v[14:15], v[14:15], v[154:155] op_sel_hi:[1,0]
	v_mul_f32_e32 v152, v152, v154

; template <int MODE>
; DI void attn_mfma(const Params& p, int l, int b, int hd, int qb, unsigned char* smem) {
;     ...
;     float mx = -1e30f;
; #pragma unroll
;     for (int mt = 0; mt < 2; ++mt)
; #pragma unroll
;       for (int i = 0; i < 16; ++i) mx = fmaxf(mx, S[mt][i]);
;     mx = fmaxf(mx, __shfl_xor(mx, 32));
;     const float zmx = mx * cexp;
;     if (__any(zmx > mrun + 8.f)) {
;       const float mnew = fmaxf(mrun, zmx);
;       const float alpha = __builtin_amdgcn_exp2f(mrun - mnew);
;       mrun = mnew;
;       lsum *= alpha;
;       const f32x2 al2 = {alpha, alpha};
; #pragma unroll
;       for (int vt = 0; vt < 2; ++vt)
; #pragma unroll
;         for (int i = 0; i < 8; ++i) {
;           f32x2 o = {O[vt][2 * i], O[vt][2 * i + 1]};
;           o = o * al2;
;           O[vt][2 * i] = o.x; O[vt][2 * i + 1] = o.y;
;         }
;     }
.Lcc_qkdone:
	ds_read2_b64 v[220:223], v213 offset1:2
	ds_read2_b64 v[224:227], v216 offset0:32 offset1:34
	ds_read2_b64 v[228:231], v213 offset0:4 offset1:6
	ds_read2_b64 v[232:235], v216 offset0:36 offset1:38
	ds_read2_b64 v[236:239], v213 offset0:8 offset1:10
	ds_read2_b64 v[240:243], v216 offset0:40 offset1:42
	ds_read2_b64 v[244:247], v213 offset0:12 offset1:14
	ds_read2_b64 v[248:251], v216 offset0:44 offset1:46
	v_max3_f32 v204, v80, s2, v81
	v_max3_f32 v204, v204, v82, v83
	v_max3_f32 v204, v204, v84, v85
	v_max3_f32 v204, v204, v86, v87
	v_max3_f32 v204, v204, v88, v89
	v_max3_f32 v204, v204, v90, v91
	v_max3_f32 v204, v204, v92, v93
	v_max3_f32 v204, v204, v94, v95
	v_max3_f32 v204, v204, v64, v65
	v_max3_f32 v204, v204, v66, v67
	v_max3_f32 v204, v204, v68, v69
	v_max3_f32 v204, v204, v70, v71
	v_max3_f32 v204, v204, v72, v73
	v_max3_f32 v204, v204, v74, v75
	v_max3_f32 v204, v204, v76, v77
	v_max3_f32 v204, v204, v78, v79
	v_mov_b32_e32 v205, v204
	s_nop 1
	v_permlane32_swap_b32_e32 v205, v204
	s_waitcnt lgkmcnt(0)
	v_max_f32_e32 v204, v204, v205
	v_mul_f32_e32 v204, 0x3e38aa3b, v204
	v_add_f32_e32 v206, 0x41000000, v166
	v_cmp_gt_f32_e32 vcc, v204, v206
	s_cbranch_vccz .Lcc_nra
	v_max_f32_e32 v204, v204, v204
	v_max_f32_e32 v205, v166, v166
	v_max_f32_e32 v204, v205, v204
	v_sub_f32_e32 v166, v166, v204
	v_exp_f32_e32 v166, v166
	s_nop 0
	v_pk_mul_f32 v[18:19], v[18:19], v[166:167] op_sel_hi:[1,0]
	v_pk_mul_f32 v[20:21], v[20:21], v[166:167] op_sel_hi:[1,0]
	v_pk_mul_f32 v[22:23], v[22:23], v[166:167] op_sel_hi:[1,0]
	v_pk_mul_f32 v[24:25], v[24:25], v[166:167] op_sel_hi:[1,0]
	v_pk_mul_f32 v[26:27], v[26:27], v[166:167] op_sel_hi:[1,0]
	v_pk_mul_f32 v[28:29], v[28:29], v[166:167] op_sel_hi:[1,0]
	v_pk_mul_f32 v[16:17], v[16:17], v[166:167] op_sel_hi:[1,0]
	v_pk_mul_f32 v[30:31], v[30:31], v[166:167] op_sel_hi:[1,0]
	v_pk_mul_f32 v[0:1], v[0:1], v[166:167] op_sel_hi:[1,0]
	v_pk_mul_f32 v[2:3], v[2:3], v[166:167] op_sel_hi:[1,0]
	v_pk_mul_f32 v[4:5], v[4:5], v[166:167] op_sel_hi:[1,0]
	v_pk_mul_f32 v[6:7], v[6:7], v[166:167] op_sel_hi:[1,0]
	v_pk_mul_f32 v[8:9], v[8:9], v[166:167] op_sel_hi:[1,0]
	v_pk_mul_f32 v[10:11], v[10:11], v[166:167] op_sel_hi:[1,0]
	v_pk_mul_f32 v[12:13], v[12:13], v[166:167] op_sel_hi:[1,0]
	v_pk_mul_f32 v[14:15], v[14:15], v[166:167] op_sel_hi:[1,0]
	v_mul_f32_e32 v200, v200, v166
	v_mov_b32_e32 v166, v204

; template <int MODE>
; DI void attn_mfma(const Params& p, int l, int b, int hd, int qb, unsigned char* smem) {
;     ...
;     float mx = -1e30f;
; #pragma unroll
;     for (int mt = 0; mt < 2; ++mt)
; #pragma unroll
;       for (int i = 0; i < 16; ++i) mx = fmaxf(mx, S[mt][i]);
;     mx = fmaxf(mx, __shfl_xor(mx, 32));
;     const float zmx = mx * cexp;
;     if (__any(zmx > mrun + 8.f)) {
;       const float mnew = fmaxf(mrun, zmx);
;       const float alpha = __builtin_amdgcn_exp2f(mrun - mnew);
;       mrun = mnew;
;       lsum *= alpha;
;       const f32x2 al2 = {alpha, alpha};
; #pragma unroll
;       for (int vt = 0; vt < 2; ++vt)
; #pragma unroll
;         for (int i = 0; i < 8; ++i) {
;           f32x2 o = {O[vt][2 * i], O[vt][2 * i + 1]};
;           o = o * al2;
;           O[vt][2 * i] = o.x; O[vt][2 * i + 1] = o.y;
;         }
;     }
.Lcc_nomaskB:
	v_max3_f32 v210, v48, s2, v49
	v_max3_f32 v210, v210, v50, v51
	v_max3_f32 v210, v210, v52, v53
	v_max3_f32 v210, v210, v54, v55
	v_max3_f32 v210, v210, v56, v57
	v_max3_f32 v210, v210, v58, v59
	v_max3_f32 v210, v210, v60, v61
	v_max3_f32 v210, v210, v62, v63
	v_mfma_f32_32x32x16_bf16 v[0:15], v[248:251], v[64:67], v[0:15]
	v_max3_f32 v210, v210, v32, v33
	v_max3_f32 v210, v210, v34, v35
	v_max3_f32 v210, v210, v36, v37
	v_max3_f32 v210, v210, v38, v39
	v_max3_f32 v210, v210, v40, v41
	v_max3_f32 v210, v210, v42, v43
	v_max3_f32 v210, v210, v44, v45
	v_max3_f32 v210, v210, v46, v47
	v_mov_b32_e32 v211, v210
	s_nop 1
	v_permlane32_swap_b32_e32 v211, v210
	ds_read2_b64 v[220:223], v217 offset0:64 offset1:66
	ds_read2_b64 v[224:227], v218 offset0:96 offset1:98
	ds_read2_b64 v[228:231], v217 offset0:68 offset1:70
	ds_read2_b64 v[232:235], v218 offset0:100 offset1:102
	ds_read2_b64 v[236:239], v217 offset0:72 offset1:74
	ds_read2_b64 v[240:243], v218 offset0:104 offset1:106
	ds_read2_b64 v[244:247], v217 offset0:76 offset1:78
	ds_read2_b64 v[248:251], v218 offset0:108 offset1:110
	s_waitcnt lgkmcnt(8)
	v_max_f32_e32 v210, v210, v211
	v_mul_f32_e32 v210, 0x3e38aa3b, v210
	v_add_f32_e32 v211, 0x41000000, v166
	v_cmp_gt_f32_e32 vcc, v210, v211
	s_cbranch_vccz .Lcc_nrb
	v_max_f32_e32 v210, v210, v210
	v_max_f32_e32 v211, v166, v166
	v_max_f32_e32 v210, v211, v210
	v_sub_f32_e32 v211, v166, v210
	v_exp_f32_e32 v214, v211
	v_mov_b32_e32 v166, v210
	v_pk_mul_f32 v[16:17], v[16:17], v[214:215] op_sel_hi:[1,0]
	v_pk_mul_f32 v[18:19], v[18:19], v[214:215] op_sel_hi:[1,0]
	v_pk_mul_f32 v[20:21], v[20:21], v[214:215] op_sel_hi:[1,0]
	v_pk_mul_f32 v[22:23], v[22:23], v[214:215] op_sel_hi:[1,0]
	v_pk_mul_f32 v[24:25], v[24:25], v[214:215] op_sel_hi:[1,0]
	v_pk_mul_f32 v[26:27], v[26:27], v[214:215] op_sel_hi:[1,0]
	v_pk_mul_f32 v[28:29], v[28:29], v[214:215] op_sel_hi:[1,0]
	v_pk_mul_f32 v[30:31], v[30:31], v[214:215] op_sel_hi:[1,0]
	v_pk_mul_f32 v[0:1], v[0:1], v[214:215] op_sel_hi:[1,0]
	v_pk_mul_f32 v[2:3], v[2:3], v[214:215] op_sel_hi:[1,0]
	v_pk_mul_f32 v[4:5], v[4:5], v[214:215] op_sel_hi:[1,0]
	v_pk_mul_f32 v[6:7], v[6:7], v[214:215] op_sel_hi:[1,0]
	v_pk_mul_f32 v[8:9], v[8:9], v[214:215] op_sel_hi:[1,0]
	v_pk_mul_f32 v[10:11], v[10:11], v[214:215] op_sel_hi:[1,0]
	v_pk_mul_f32 v[12:13], v[12:13], v[214:215] op_sel_hi:[1,0]
	v_pk_mul_f32 v[14:15], v[14:15], v[214:215] op_sel_hi:[1,0]
	v_mul_f32_e32 v212, v212, v214
